# cache policy: f32 weight tile loads in the prologue and the once-read bf16 GEMM-output rows in the row updates are loaded non-temporal
# speedup vs baseline: 1.0248x; 1.0154x over previous
.LBB0_28:
	v_lshl_add_u64 v[0:1], v[32:33], 0, v[30:31]
	global_load_dwordx2 v[12:13], v[0:1], off nt
	global_load_dwordx2 v[14:15], v[0:1], off offset:1536 nt
	global_load_dwordx2 v[36:37], v[0:1], off offset:512 nt
	global_load_dwordx2 v[38:39], v[0:1], off offset:1024 nt
	v_readlane_b32 s8, v254, 9
	v_readlane_b32 s48, v254, 38
	v_readlane_b32 s20, v254, 21
	v_readlane_b32 s21, v254, 22
	v_readlane_b32 s52, v254, 42
	v_readlane_b32 s53, v254, 43
	v_cmp_gt_i32_e32 vcc, s68, v16
	v_mov_b32_e32 v8, s21
	v_mov_b32_e32 v9, s53
	v_mov_b32_e32 v10, s20
	v_mov_b32_e32 v11, s52
	v_min_i32_e32 v40, 0x4000, v16
	v_readlane_b32 s12, v254, 13
	v_readlane_b32 s13, v254, 14
	v_cndmask_b32_e32 v9, v8, v9, vcc
	v_cndmask_b32_e32 v8, v10, v11, vcc
	v_ashrrev_i32_e32 v10, 13, v40
	s_mul_i32 s3, s24, 3
	v_add_u32_e32 v4, 0xffffc000, v16
	v_readlane_b32 s10, v254, 11
	v_readlane_b32 s11, v254, 12
	v_mov_b64_e32 v[6:7], s[12:13]
	v_add_u32_e32 v40, s3, v10
	v_cndmask_b32_e32 v5, 0, v17, vcc
	v_cndmask_b32_e32 v4, v4, v16, vcc
	v_mad_i64_i32 v[6:7], s[10:11], v40, s67, v[6:7]
	v_lshlrev_b64 v[4:5], 12, v[4:5]
	s_mov_b64 s[10:11], 0x5000
	v_lshlrev_b32_e32 v192, 2, v18
	v_lshl_add_u64 v[4:5], v[8:9], 0, v[4:5]
	v_lshl_add_u64 v[56:57], v[6:7], 0, s[10:11]
	global_load_dwordx4 v[0:3], v[26:27], off
	v_lshl_add_u64 v[54:55], v[4:5], 0, v[192:193]
	v_lshl_add_u64 v[8:9], v[56:57], 0, v[192:193]
	global_load_dwordx4 v[4:7], v[54:55], off
	s_andn2_b64 vcc, exec, s[38:39]
	global_load_dwordx4 v[8:11], v[8:9], off
	v_lshl_add_u64 v[96:97], v[56:57], 0, v[192:193]
	global_load_dwordx4 v[100:103], v[54:55], off offset:1024
	global_load_dwordx4 v[112:115], v[26:27], off offset:1024
	global_load_dwordx4 v[124:127], v[96:97], off offset:1024
	global_load_dwordx4 v[104:107], v[54:55], off offset:2048
	global_load_dwordx4 v[116:119], v[26:27], off offset:2048
	global_load_dwordx4 v[128:131], v[96:97], off offset:2048
	global_load_dwordx4 v[120:123], v[26:27], off offset:3072
	global_load_dwordx4 v[108:111], v[54:55], off offset:3072
	global_load_dwordx4 v[132:135], v[96:97], off offset:3072
	v_readlane_b32 s9, v254, 10
	v_readlane_b32 s14, v254, 15
	v_readlane_b32 s15, v254, 16
	v_readlane_b32 s16, v254, 17
	v_readlane_b32 s17, v254, 18
	v_readlane_b32 s18, v254, 19
	v_readlane_b32 s19, v254, 20
	v_readlane_b32 s22, v254, 23
	v_readlane_b32 s23, v254, 24
	v_readlane_b32 s49, v254, 39
	v_readlane_b32 s50, v254, 40
	v_readlane_b32 s51, v254, 41
	v_readlane_b32 s54, v254, 44
	v_readlane_b32 s55, v254, 45
	v_readlane_b32 s56, v254, 46
	v_readlane_b32 s57, v254, 47
	v_readlane_b32 s58, v254, 48
	v_readlane_b32 s59, v254, 49
	v_readlane_b32 s60, v254, 50
	v_readlane_b32 s61, v254, 51
	v_readlane_b32 s62, v254, 52
	v_readlane_b32 s63, v254, 53
	s_waitcnt vmcnt(15)
	v_lshlrev_b32_e32 v52, 16, v12
	v_and_b32_e32 v53, 0xffff0000, v12
	s_waitcnt vmcnt(13)
	v_lshlrev_b32_e32 v62, 16, v36
	v_and_b32_e32 v63, 0xffff0000, v36
	s_waitcnt vmcnt(12)
	v_and_b32_e32 v67, 0xffff0000, v38
	v_and_b32_e32 v69, 0xffff0000, v14
	v_lshlrev_b32_e32 v50, 16, v13
	v_and_b32_e32 v51, 0xffff0000, v13
	v_and_b32_e32 v59, 0xffff0000, v15
	v_lshlrev_b32_e32 v58, 16, v15
	v_lshlrev_b32_e32 v60, 16, v37
	v_and_b32_e32 v61, 0xffff0000, v37
	v_lshlrev_b32_e32 v64, 16, v39
	v_and_b32_e32 v65, 0xffff0000, v39
	v_lshlrev_b32_e32 v66, 16, v38
	v_lshlrev_b32_e32 v68, 16, v14
	v_pk_mul_f32 v[14:15], v[52:53], v[52:53]
	v_pk_mul_f32 v[38:39], v[62:63], v[62:63]
	v_mov_b32_e32 v70, v67
	v_mov_b32_e32 v71, v69
	v_pk_mul_f32 v[12:13], v[50:51], v[50:51]
	v_pk_mul_f32 v[36:37], v[60:61], v[60:61]
	v_mov_b32_e32 v46, v66
	v_mov_b32_e32 v47, v68
	v_pk_mul_f32 v[70:71], v[70:71], v[70:71]
	v_add_f32_e32 v38, v38, v39
	v_add_f32_e32 v39, v14, v15
	v_mov_b32_e32 v42, v64
	v_mov_b32_e32 v43, v58
	v_pk_fma_f32 v[14:15], v[46:47], v[46:47], v[70:71]
	v_add_f32_e32 v36, v36, v38
	v_add_f32_e32 v12, v12, v39
	v_mov_b32_e32 v44, v65
	v_mov_b32_e32 v45, v59
	v_pk_fma_f32 v[14:15], v[42:43], v[42:43], v[14:15]
	v_add_f32_e32 v36, v37, v36
	v_add_f32_e32 v37, v13, v12
	v_pk_fma_f32 v[12:13], v[44:45], v[44:45], v[14:15]
	v_add_f32_e32 v14, v37, v36
	v_add_f32_e32 v12, v14, v12
	v_add_f32_e32 v12, v12, v13
	v_lshlrev_b32_e32 v42, 2, v20
	v_mov_b32_e32 v43, v193
	s_nop 0
	v_lshlrev_b32_e32 v38, 2, v22
	s_waitcnt lgkmcnt(0)
	v_mov_b32_e32 v13, v12
	s_nop 1
	v_permlane32_swap_b32_e32 v13, v12
	v_add_f32_e32 v12, v12, v13
	v_mov_b32_e32 v39, v193
	v_lshlrev_b32_e32 v36, 2, v24
	v_mov_b32_e32 v37, v193
	v_mov_b32_e32 v13, v12
	s_nop 1
	v_permlane16_swap_b32_e32 v13, v12
	v_add_f32_e32 v12, v12, v13
	s_nop 1
	v_add_f32_dpp v12, v12, v12 row_ror:8 row_mask:0xf bank_mask:0xf
	s_nop 1
	v_add_f32_dpp v12, v12, v12 row_ror:4 row_mask:0xf bank_mask:0xf
	s_nop 1
	v_add_f32_dpp v12, v12, v12 row_ror:2 row_mask:0xf bank_mask:0xf
	s_nop 1
	v_add_f32_dpp v12, v12, v12 row_ror:1 row_mask:0xf bank_mask:0xf
	v_fmamk_f32 v12, v12, 0x3a800000, v221
	v_rsq_f32_e32 v70, v12
	s_nop 0
	v_pk_mul_f32 v[12:13], v[70:71], v[52:53] op_sel_hi:[0,1]
	v_pk_mul_f32 v[14:15], v[70:71], v[50:51] op_sel_hi:[0,1]
	s_waitcnt vmcnt(11)
	v_pk_mul_f32 v[0:1], v[0:1], v[12:13]
	v_pk_mul_f32 v[2:3], v[2:3], v[14:15]
	s_waitcnt vmcnt(9)
	v_pk_fma_f32 v[12:13], v[8:9], v[0:1], v[4:5]
	v_pk_fma_f32 v[14:15], v[10:11], v[2:3], v[6:7]
	global_store_dwordx4 v[54:55], v[12:15], off
	s_nop 0
	v_lshl_add_u64 v[4:5], v[56:57], 0, v[42:43]
	s_nop 0
	v_pk_mul_f32 v[8:9], v[70:71], v[62:63] op_sel_hi:[0,1]
	v_pk_mul_f32 v[10:11], v[70:71], v[60:61] op_sel_hi:[0,1]
	s_nop 0
	v_pk_mul_f32 v[60:61], v[70:71], v[66:67] op_sel_hi:[0,1]
	v_pk_mul_f32 v[62:63], v[70:71], v[64:65] op_sel_hi:[0,1]
	v_pk_mul_f32 v[58:59], v[70:71], v[58:59] op_sel_hi:[0,1]
	s_waitcnt vmcnt(8)
	v_pk_mul_f32 v[0:1], v[112:113], v[8:9]
	v_pk_mul_f32 v[2:3], v[114:115], v[10:11]
	s_waitcnt vmcnt(7)
	v_pk_fma_f32 v[8:9], v[124:125], v[0:1], v[100:101]
	v_pk_fma_f32 v[10:11], v[126:127], v[2:3], v[102:103]
	global_store_dwordx4 v[54:55], v[8:11], off offset:1024
	s_nop 0
	v_lshl_add_u64 v[4:5], v[56:57], 0, v[38:39]
	s_nop 0
	s_waitcnt vmcnt(6)
	v_pk_mul_f32 v[0:1], v[116:117], v[60:61]
	v_pk_mul_f32 v[2:3], v[118:119], v[62:63]
	s_waitcnt vmcnt(5)
	v_pk_fma_f32 v[4:5], v[128:129], v[0:1], v[104:105]
	v_pk_fma_f32 v[6:7], v[130:131], v[2:3], v[106:107]
	global_store_dwordx4 v[54:55], v[4:7], off offset:2048
	s_nop 0
	v_lshl_add_u64 v[50:51], v[56:57], 0, v[36:37]
	s_nop 0
	v_pk_mul_f32 v[56:57], v[70:71], v[68:69] op_sel_hi:[0,1]
	s_nop 0
	s_waitcnt vmcnt(5)
	v_pk_mul_f32 v[0:1], v[56:57], v[120:121]
	v_pk_mul_f32 v[2:3], v[58:59], v[122:123]
	s_waitcnt vmcnt(3)
	v_pk_fma_f32 v[0:1], v[132:133], v[0:1], v[108:109]
	v_pk_fma_f32 v[2:3], v[134:135], v[2:3], v[110:111]
	global_store_dwordx4 v[54:55], v[0:3], off offset:3072
	s_cbranch_vccnz .LBB0_27
	v_pk_mul_f32 v[44:45], v[12:13], v[12:13]
	v_pk_mul_f32 v[46:47], v[14:15], v[14:15]
	v_add_f32_e32 v44, v44, v45
	v_add_f32_e32 v44, v46, v44
	v_pk_mul_f32 v[50:51], v[8:9], v[8:9]
	v_add_f32_e32 v44, v47, v44
	v_add_f32_e32 v44, v50, v44
	v_pk_mul_f32 v[52:53], v[10:11], v[10:11]
	v_add_f32_e32 v44, v51, v44
	v_add_f32_e32 v44, v52, v44
	v_pk_mul_f32 v[54:55], v[4:5], v[4:5]
	v_add_f32_e32 v44, v53, v44
	v_add_f32_e32 v44, v54, v44
	v_pk_mul_f32 v[56:57], v[6:7], v[6:7]
	v_add_f32_e32 v44, v55, v44
	v_add_f32_e32 v44, v56, v44
	v_pk_mul_f32 v[58:59], v[0:1], v[0:1]
	v_add_f32_e32 v44, v57, v44
	v_add_f32_e32 v44, v58, v44
	v_pk_mul_f32 v[60:61], v[2:3], v[2:3]
	v_add_f32_e32 v44, v59, v44
	v_add_f32_e32 v44, v60, v44
	v_add_f32_e32 v44, v61, v44
	v_readlane_b32 s8, v254, 9
	v_readlane_b32 s12, v254, 13
	v_readlane_b32 s13, v254, 14
	v_add_u32_e32 v40, 3, v40
	s_waitcnt lgkmcnt(0)
	v_mov_b32_e32 v45, v44
	s_nop 1
	v_permlane32_swap_b32_e32 v45, v44
	v_add_f32_e32 v44, v44, v45
	v_readlane_b32 s10, v254, 11
	v_readlane_b32 s11, v254, 12
	global_load_dwordx4 v[50:53], v[28:29], off
	v_readlane_b32 s9, v254, 10
	v_mov_b32_e32 v45, v44
	s_nop 1
	v_permlane16_swap_b32_e32 v45, v44
	v_add_f32_e32 v44, v44, v45
	v_readlane_b32 s14, v254, 15
	v_readlane_b32 s15, v254, 16
	v_readlane_b32 s16, v254, 17
	v_readlane_b32 s17, v254, 18
	s_nop 1
	v_add_f32_dpp v44, v44, v44 row_ror:8 row_mask:0xf bank_mask:0xf
	v_readlane_b32 s18, v254, 19
	v_readlane_b32 s19, v254, 20
	v_readlane_b32 s20, v254, 21
	v_readlane_b32 s21, v254, 22
	s_nop 1
	v_add_f32_dpp v44, v44, v44 row_ror:4 row_mask:0xf bank_mask:0xf
	v_readlane_b32 s22, v254, 23
	v_readlane_b32 s23, v254, 24
	s_nop 1
	v_add_f32_dpp v44, v44, v44 row_ror:2 row_mask:0xf bank_mask:0xf
	s_nop 1
	v_add_f32_dpp v49, v44, v44 row_ror:1 row_mask:0xf bank_mask:0xf
	v_mov_b64_e32 v[44:45], s[12:13]
	v_mad_i64_i32 v[44:45], s[10:11], v40, s67, v[44:45]
	v_lshl_add_u64 v[46:47], v[44:45], 0, s[34:35]
	v_lshl_add_u64 v[54:55], v[46:47], 0, v[192:193]
	global_load_dwordx4 v[54:57], v[54:55], off
	v_lshl_add_u64 v[44:45], v[44:45], 0, v[192:193]
	global_load_dwordx4 v[58:61], v[44:45], off
	v_lshl_add_u64 v[98:99], v[46:47], 0, v[192:193]
	global_load_dwordx4 v[140:143], v[28:29], off offset:1024
	global_load_dwordx4 v[152:155], v[98:99], off offset:1024
	global_load_dwordx4 v[164:167], v[44:45], off offset:1024
	global_load_dwordx4 v[144:147], v[28:29], off offset:2048
	global_load_dwordx4 v[156:159], v[98:99], off offset:2048
	global_load_dwordx4 v[168:171], v[44:45], off offset:2048
	global_load_dwordx4 v[148:151], v[28:29], off offset:3072
	global_load_dwordx4 v[160:163], v[98:99], off offset:3072
	global_load_dwordx4 v[172:175], v[44:45], off offset:3072
	v_fmamk_f32 v40, v49, 0x3a800000, v221
	v_rsq_f32_e32 v40, v40
	s_nop 0
	v_pk_mul_f32 v[12:13], v[12:13], v[40:41] op_sel_hi:[1,0]
	v_pk_mul_f32 v[14:15], v[14:15], v[40:41] op_sel_hi:[1,0]
	v_pk_mul_f32 v[8:9], v[8:9], v[40:41] op_sel_hi:[1,0]
	v_pk_mul_f32 v[10:11], v[10:11], v[40:41] op_sel_hi:[1,0]
	v_pk_mul_f32 v[4:5], v[4:5], v[40:41] op_sel_hi:[1,0]
	v_pk_mul_f32 v[6:7], v[6:7], v[40:41] op_sel_hi:[1,0]
	v_pk_mul_f32 v[0:1], v[0:1], v[40:41] op_sel_hi:[1,0]
	v_pk_mul_f32 v[2:3], v[2:3], v[40:41] op_sel_hi:[1,0]
	s_waitcnt vmcnt(11)
	v_pk_mul_f32 v[12:13], v[50:51], v[12:13]
	v_pk_mul_f32 v[14:15], v[52:53], v[14:15]
	s_waitcnt vmcnt(10)
	v_pk_add_f32 v[50:51], v[54:55], 1.0 op_sel_hi:[1,0]
	s_waitcnt vmcnt(9)
	v_pk_fma_f32 v[12:13], v[50:51], v[12:13], v[58:59]
	v_pk_add_f32 v[50:51], v[56:57], 1.0 op_sel_hi:[1,0]
	s_nop 0
	v_pk_fma_f32 v[14:15], v[50:51], v[14:15], v[60:61]
	v_cvt_pk_bf16_f32 v50, v12, v13
	v_cvt_pk_bf16_f32 v51, v14, v15
	v_lshl_add_u64 v[12:13], v[34:35], 0, v[30:31]
	global_store_dwordx2 v[12:13], v[50:51], off
	s_nop 0
	v_lshl_add_u64 v[14:15], v[46:47], 0, v[42:43]
	s_nop 0
	s_nop 0
	s_waitcnt vmcnt(9)
	v_pk_mul_f32 v[8:9], v[8:9], v[140:141]
	s_waitcnt vmcnt(8)
	v_pk_add_f32 v[14:15], v[152:153], 1.0 op_sel_hi:[1,0]
	v_pk_mul_f32 v[10:11], v[10:11], v[142:143]
	s_waitcnt vmcnt(7)
	v_pk_fma_f32 v[8:9], v[8:9], v[14:15], v[164:165]
	v_pk_add_f32 v[14:15], v[154:155], 1.0 op_sel_hi:[1,0]
	v_cvt_pk_bf16_f32 v8, v8, v9
	v_pk_fma_f32 v[10:11], v[10:11], v[14:15], v[166:167]
	v_lshl_add_u64 v[14:15], v[46:47], 0, v[38:39]
	v_cvt_pk_bf16_f32 v9, v10, v11
	global_store_dwordx2 v[12:13], v[8:9], off offset:512
	s_nop 0
	s_nop 0
	s_nop 0
	s_nop 0
	s_waitcnt vmcnt(7)
	v_pk_mul_f32 v[4:5], v[4:5], v[144:145]
	s_waitcnt vmcnt(6)
	v_pk_add_f32 v[8:9], v[156:157], 1.0 op_sel_hi:[1,0]
	v_pk_mul_f32 v[6:7], v[6:7], v[146:147]
	s_waitcnt vmcnt(5)
	v_pk_fma_f32 v[4:5], v[4:5], v[8:9], v[168:169]
	v_pk_add_f32 v[8:9], v[158:159], 1.0 op_sel_hi:[1,0]
	v_cvt_pk_bf16_f32 v4, v4, v5
	v_pk_fma_f32 v[6:7], v[6:7], v[8:9], v[170:171]
	v_lshl_add_u64 v[8:9], v[46:47], 0, v[36:37]
	v_cvt_pk_bf16_f32 v5, v6, v7
	global_store_dwordx2 v[12:13], v[4:5], off offset:1024
	s_nop 0
	s_nop 0
	s_nop 0
	s_nop 0
	s_nop 0
	s_waitcnt vmcnt(5)
	v_pk_mul_f32 v[0:1], v[0:1], v[148:149]
	s_waitcnt vmcnt(4)
	v_pk_add_f32 v[4:5], v[160:161], 1.0 op_sel_hi:[1,0]
	v_pk_mul_f32 v[2:3], v[2:3], v[150:151]
	s_waitcnt vmcnt(3)
	v_pk_fma_f32 v[0:1], v[0:1], v[4:5], v[172:173]
	v_pk_add_f32 v[4:5], v[162:163], 1.0 op_sel_hi:[1,0]
	v_cvt_pk_bf16_f32 v0, v0, v1
	v_pk_fma_f32 v[2:3], v[2:3], v[4:5], v[174:175]
	s_nop 0
	v_cvt_pk_bf16_f32 v1, v2, v3
	global_store_dwordx2 v[12:13], v[0:1], off offset:1536
	s_branch .LBB0_27

.LBB0_71:
	v_readlane_b32 s8, v253, 56
	v_readlane_b32 s12, v253, 60
	v_cmp_gt_i32_e64 s[0:1], s3, v24
	v_mov_b32_e32 v3, s8
	s_mov_b32 s8, s54
	v_readlane_b32 s48, v254, 9
	v_readlane_b32 s9, v253, 57
	v_readlane_b32 s10, v253, 58
	v_readlane_b32 s11, v253, 59
	v_readlane_b32 s13, v253, 61
	v_readlane_b32 s14, v253, 62
	v_readlane_b32 s15, v253, 63
	v_readlane_b32 s16, v254, 0
	v_readlane_b32 s17, v254, 1
	v_readlane_b32 s18, v254, 2
	v_readlane_b32 s19, v254, 3
	v_readlane_b32 s20, v254, 4
	v_readlane_b32 s21, v254, 5
	v_readlane_b32 s22, v254, 6
	v_readlane_b32 s23, v254, 7
	v_mov_b32_e32 v2, s12
	v_readlane_b32 s54, v254, 15
	v_cndmask_b32_e64 v2, v2, v3, s[0:1]
	v_mov_b32_e32 v3, s13
	v_mov_b32_e32 v4, s9
	s_mov_b32 s54, s8
	v_readlane_b32 s8, v254, 38
	v_readlane_b32 s61, v254, 22
	v_readlane_b32 s13, v254, 43
	v_cndmask_b32_e64 v3, v3, v4, s[0:1]
	v_readlane_b32 s60, v254, 21
	v_mov_b32_e32 v4, s61
	v_readlane_b32 s12, v254, 42
	v_mov_b32_e32 v5, s13
	v_add_u32_e32 v0, 0xffffc000, v24
	v_cndmask_b32_e64 v17, v4, v5, s[0:1]
	v_mov_b32_e32 v4, s60
	v_mov_b32_e32 v5, s12
	v_cndmask_b32_e64 v1, 0, v25, s[0:1]
	v_cndmask_b32_e64 v0, v0, v24, s[0:1]
	v_cndmask_b32_e64 v16, v4, v5, s[0:1]
	v_cndmask_b32_e32 v3, v17, v3, vcc
	v_cndmask_b32_e32 v2, v16, v2, vcc
	v_lshlrev_b64 v[18:19], 12, v[0:1]
	v_lshl_add_u64 v[0:1], v[2:3], 0, v[18:19]
	v_min_i32_e32 v2, 0x4000, v24
	v_readlane_b32 s52, v254, 13
	v_readlane_b32 s53, v254, 14
	v_ashrrev_i32_e32 v2, 13, v2
	s_mul_i32 s0, s54, 3
	v_add_u32_e32 v4, s0, v2
	v_mov_b64_e32 v[2:3], s[52:53]
	v_mad_i64_i32 v[42:43], s[0:1], v4, s67, v[2:3]
	v_lshl_add_u64 v[4:5], v[32:33], 0, v[30:31]
	v_lshl_add_u64 v[6:7], v[0:1], 0, v[192:193]
	global_load_dwordx2 v[54:55], v[4:5], off nt
	global_load_dwordx4 v[12:15], v[6:7], off nt
	global_load_dwordx2 v[58:59], v[4:5], off offset:512 nt
	global_load_dwordx4 v[8:11], v[6:7], off offset:1024 nt
	global_load_dwordx2 v[20:21], v[4:5], off offset:1024 nt
	global_load_dwordx4 v[0:3], v[6:7], off offset:2048 nt
	global_load_dwordx2 v[22:23], v[4:5], off offset:1536 nt
	s_nop 0
	global_load_dwordx4 v[4:7], v[6:7], off offset:3072 nt
	v_lshl_add_u64 v[96:97], v[42:43], 0, v[192:193]
	s_mov_b64 s[0:1], 0x2000
	v_lshl_add_u64 v[98:99], v[96:97], 0, s[0:1]
	s_mov_b64 s[0:1], 0x3000
	v_lshl_add_u64 v[100:101], v[96:97], 0, s[0:1]
	s_mov_b64 s[0:1], 0x4000
	v_lshl_add_u64 v[102:103], v[96:97], 0, s[0:1]
	global_load_dwordx4 v[104:107], v[98:99], off
	global_load_dwordx4 v[120:123], v[26:27], off
	global_load_dwordx4 v[108:111], v[98:99], off offset:1024
	global_load_dwordx4 v[124:127], v[26:27], off offset:1024
	global_load_dwordx4 v[112:115], v[98:99], off offset:2048
	global_load_dwordx4 v[128:131], v[26:27], off offset:2048
	global_load_dwordx4 v[116:119], v[98:99], off offset:3072
	global_load_dwordx4 v[132:135], v[26:27], off offset:3072
	global_load_dwordx4 v[136:139], v[102:103], off
	global_load_dwordx4 v[152:155], v[100:101], off
	global_load_dwordx4 v[168:171], v[28:29], off
	global_load_dwordx4 v[172:175], v[28:29], off offset:1024
	global_load_dwordx4 v[140:143], v[102:103], off offset:1024
	global_load_dwordx4 v[156:159], v[100:101], off offset:1024
	global_load_dwordx4 v[176:179], v[28:29], off offset:2048
	global_load_dwordx4 v[144:147], v[102:103], off offset:2048
	global_load_dwordx4 v[160:163], v[100:101], off offset:2048
	global_load_dwordx4 v[180:183], v[28:29], off offset:3072
	global_load_dwordx4 v[148:151], v[102:103], off offset:3072
	global_load_dwordx4 v[164:167], v[100:101], off offset:3072
	s_mov_b64 s[0:1], 0x2000
	v_lshl_add_u64 v[52:53], v[42:43], 0, s[0:1]
	v_lshl_add_u64 v[72:73], v[16:17], 0, v[18:19]
	v_lshl_add_u64 v[16:17], v[52:53], 0, v[192:193]
	v_mov_b32_e32 v37, v193
	s_mov_b64 s[0:1], 0x4000
	v_lshl_add_u64 v[24:25], v[24:25], 0, s[40:41]
	v_lshl_add_u64 v[32:33], v[32:33], 0, s[42:43]
	v_readlane_b32 s49, v254, 10
	v_readlane_b32 s50, v254, 11
	v_readlane_b32 s51, v254, 12
	v_readlane_b32 s55, v254, 16
	v_readlane_b32 s56, v254, 17
	v_readlane_b32 s57, v254, 18
	v_readlane_b32 s58, v254, 19
	v_readlane_b32 s59, v254, 20
	v_readlane_b32 s62, v254, 23
	v_readlane_b32 s63, v254, 24
	v_readlane_b32 s9, v254, 39
	v_readlane_b32 s10, v254, 40
	v_readlane_b32 s11, v254, 41
	v_readlane_b32 s14, v254, 44
	v_readlane_b32 s15, v254, 45
	v_readlane_b32 s16, v254, 46
	v_readlane_b32 s17, v254, 47
	v_readlane_b32 s18, v254, 48
	v_readlane_b32 s19, v254, 49
	v_readlane_b32 s20, v254, 50
	v_readlane_b32 s21, v254, 51
	v_readlane_b32 s22, v254, 52
	v_readlane_b32 s23, v254, 53
	s_waitcnt vmcnt(27)
	v_lshlrev_b32_e32 v62, 16, v54
	v_and_b32_e32 v63, 0xffff0000, v54
	s_waitcnt vmcnt(25)
	v_lshlrev_b32_e32 v76, 16, v58
	v_and_b32_e32 v77, 0xffff0000, v58
	s_waitcnt vmcnt(23)
	v_and_b32_e32 v50, 0xffff0000, v20
	v_lshlrev_b32_e32 v48, 16, v20
	s_waitcnt vmcnt(21)
	v_and_b32_e32 v51, 0xffff0000, v22
	v_lshlrev_b32_e32 v49, 16, v22
	v_lshlrev_b32_e32 v44, 16, v21
	v_and_b32_e32 v46, 0xffff0000, v21
	v_pk_mul_f32 v[20:21], v[50:51], v[50:51]
	v_lshlrev_b32_e32 v45, 16, v23
	v_pk_fma_f32 v[20:21], v[48:49], v[48:49], v[20:21]
	v_and_b32_e32 v47, 0xffff0000, v23
	v_pk_fma_f32 v[20:21], v[44:45], v[44:45], v[20:21]
	v_pk_mul_f32 v[74:75], v[62:63], v[62:63]
	v_pk_fma_f32 v[56:57], v[46:47], v[46:47], v[20:21]
	s_nop 0
	s_nop 0
	s_nop 0
	v_lshlrev_b32_e32 v60, 16, v55
	v_and_b32_e32 v61, 0xffff0000, v55
	v_pk_mul_f32 v[78:79], v[76:77], v[76:77]
	v_lshlrev_b32_e32 v80, 16, v59
	v_and_b32_e32 v81, 0xffff0000, v59
	v_pk_mul_f32 v[64:65], v[60:61], v[60:61]
	v_pk_mul_f32 v[58:59], v[80:81], v[80:81]
	v_add_f32_e32 v39, v78, v79
	v_add_f32_e32 v41, v74, v75
	v_add_f32_e32 v39, v58, v39
	v_add_f32_e32 v41, v64, v41
	v_add_f32_e32 v39, v59, v39
	v_add_f32_e32 v41, v65, v41
	v_add_f32_e32 v39, v41, v39
	v_add_f32_e32 v39, v39, v56
	v_add_f32_e32 v39, v39, v57
	v_lshl_add_u64 v[54:55], v[72:73], 0, v[192:193]
	v_lshl_add_u64 v[72:73], v[52:53], 0, v[36:37]
	s_waitcnt lgkmcnt(0)
	v_mov_b32_e32 v41, v39
	s_nop 1
	v_permlane32_swap_b32_e32 v41, v39
	v_add_f32_e32 v39, v39, v41
	v_mov_b32_e32 v41, v39
	s_nop 1
	v_permlane16_swap_b32_e32 v41, v39
	v_add_f32_e32 v39, v39, v41
	s_nop 1
	v_add_f32_dpp v39, v39, v39 row_ror:8 row_mask:0xf bank_mask:0xf
	s_nop 1
	v_add_f32_dpp v39, v39, v39 row_ror:4 row_mask:0xf bank_mask:0xf
	s_nop 1
	v_add_f32_dpp v39, v39, v39 row_ror:2 row_mask:0xf bank_mask:0xf
	s_nop 1
	v_add_f32_dpp v39, v39, v39 row_ror:1 row_mask:0xf bank_mask:0xf
	v_fmamk_f32 v39, v39, 0x3a800000, v221
	v_rsq_f32_e32 v56, v39
	v_mov_b32_e32 v39, v193
	v_mov_b32_e32 v41, v193
	v_pk_mul_f32 v[58:59], v[56:57], v[62:63] op_sel_hi:[0,1]
	v_pk_mul_f32 v[62:63], v[56:57], v[76:77] op_sel_hi:[0,1]
	s_waitcnt vmcnt(18)
	v_pk_mul_f32 v[20:21], v[120:121], v[58:59]
	s_nop 0
	v_pk_fma_f32 v[12:13], v[104:105], v[20:21], v[12:13]
	v_pk_mul_f32 v[20:21], v[56:57], v[60:61] op_sel_hi:[0,1]
	v_pk_mul_f32 v[20:21], v[122:123], v[20:21]
	v_pk_mul_f32 v[16:17], v[12:13], v[12:13]
	v_pk_fma_f32 v[14:15], v[106:107], v[20:21], v[14:15]
	global_store_dwordx4 v[54:55], v[12:15], off
	s_nop 0
	s_nop 0
	v_mov_b32_e32 v72, v48
	v_mov_b32_e32 v73, v50
	v_pk_mul_f32 v[72:73], v[56:57], v[72:73] op_sel_hi:[0,1]
	v_pk_mul_f32 v[18:19], v[14:15], v[14:15]
	v_add_f32_e32 v16, v16, v17
	v_add_f32_e32 v16, v18, v16
	v_add_f32_e32 v16, v19, v16
	v_mov_b32_e32 v50, v49
	v_pk_mul_f32 v[48:49], v[56:57], v[50:51] op_sel_hi:[0,1]
	s_waitcnt vmcnt(17)
	v_pk_mul_f32 v[58:59], v[124:125], v[62:63]
	s_nop 0
	v_pk_fma_f32 v[8:9], v[108:109], v[58:59], v[8:9]
	v_pk_mul_f32 v[20:21], v[56:57], v[80:81] op_sel_hi:[0,1]
	v_pk_mul_f32 v[20:21], v[126:127], v[20:21]
	v_pk_mul_f32 v[62:63], v[8:9], v[8:9]
	v_pk_fma_f32 v[10:11], v[110:111], v[20:21], v[10:11]
	global_store_dwordx4 v[54:55], v[8:11], off offset:1024
	v_lshl_add_u64 v[20:21], v[52:53], 0, v[38:39]
	s_nop 0
	s_nop 0
	s_nop 0
	v_add_f32_e32 v16, v62, v16
	v_pk_mul_f32 v[64:65], v[10:11], v[10:11]
	v_add_f32_e32 v16, v63, v16
	v_add_f32_e32 v16, v64, v16
	v_add_f32_e32 v16, v65, v16
	s_waitcnt vmcnt(16)
	v_pk_mul_f32 v[58:59], v[128:129], v[72:73]
	s_nop 0
	v_pk_fma_f32 v[0:1], v[112:113], v[58:59], v[0:1]
	v_mov_b32_e32 v20, v44
	v_mov_b32_e32 v21, v46
	v_pk_mul_f32 v[20:21], v[56:57], v[20:21] op_sel_hi:[0,1]
	v_pk_mul_f32 v[20:21], v[130:131], v[20:21]
	v_pk_mul_f32 v[72:73], v[0:1], v[0:1]
	v_pk_fma_f32 v[2:3], v[114:115], v[20:21], v[2:3]
	global_store_dwordx4 v[54:55], v[0:3], off offset:2048
	v_lshl_add_u64 v[20:21], v[52:53], 0, v[40:41]
	s_nop 0
	s_nop 0
	s_nop 0
	v_add_f32_e32 v16, v72, v16
	v_pk_mul_f32 v[74:75], v[2:3], v[2:3]
	v_mov_b32_e32 v46, v45
	v_add_f32_e32 v16, v73, v16
	v_pk_mul_f32 v[44:45], v[56:57], v[46:47] op_sel_hi:[0,1]
	v_add_f32_e32 v16, v74, v16
	v_add_f32_e32 v16, v75, v16
	s_waitcnt vmcnt(15)
	v_pk_mul_f32 v[48:49], v[48:49], v[132:133]
	s_nop 0
	v_pk_fma_f32 v[4:5], v[116:117], v[48:49], v[4:5]
	v_pk_mul_f32 v[44:45], v[44:45], v[134:135]
	v_pk_mul_f32 v[20:21], v[4:5], v[4:5]
	v_pk_fma_f32 v[6:7], v[118:119], v[44:45], v[6:7]
	v_add_f32_e32 v16, v20, v16
	v_pk_mul_f32 v[22:23], v[6:7], v[6:7]
	v_add_f32_e32 v16, v21, v16
	v_add_f32_e32 v16, v22, v16
	v_add_f32_e32 v16, v23, v16
	v_lshl_add_u64 v[44:45], v[42:43], 0, s[0:1]
	s_mov_b64 s[0:1], 0x3000
	global_store_dwordx4 v[54:55], v[4:7], off offset:3072
	v_lshl_add_u64 v[22:23], v[42:43], 0, s[0:1]
	s_waitcnt lgkmcnt(0)
	v_mov_b32_e32 v17, v16
	s_nop 1
	v_permlane32_swap_b32_e32 v17, v16
	v_add_f32_e32 v16, v16, v17
	v_lshl_add_u64 v[42:43], v[44:45], 0, v[192:193]
	s_nop 0
	v_lshl_add_u64 v[42:43], v[22:23], 0, v[192:193]
	s_nop 0
	v_mov_b32_e32 v17, v16
	s_nop 1
	v_permlane16_swap_b32_e32 v17, v16
	v_add_f32_e32 v16, v16, v17
	v_lshl_add_u64 v[42:43], v[34:35], 0, v[30:31]
	v_cmp_le_i32_e64 s[0:1], s2, v24
	v_lshl_add_u64 v[34:35], v[34:35], 0, s[42:43]
	s_or_b64 s[44:45], s[0:1], s[44:45]
	s_nop 1
	v_add_f32_dpp v16, v16, v16 row_ror:8 row_mask:0xf bank_mask:0xf
	s_nop 1
	v_add_f32_dpp v16, v16, v16 row_ror:4 row_mask:0xf bank_mask:0xf
	s_nop 1
	v_add_f32_dpp v16, v16, v16 row_ror:2 row_mask:0xf bank_mask:0xf
	s_nop 1
	v_add_f32_dpp v16, v16, v16 row_ror:1 row_mask:0xf bank_mask:0xf
	v_fmamk_f32 v16, v16, 0x3a800000, v221
	v_rsq_f32_e32 v20, v16
	s_nop 0
	v_pk_mul_f32 v[12:13], v[12:13], v[20:21] op_sel_hi:[1,0]
	v_pk_mul_f32 v[14:15], v[14:15], v[20:21] op_sel_hi:[1,0]
	v_pk_mul_f32 v[8:9], v[8:9], v[20:21] op_sel_hi:[1,0]
	v_pk_mul_f32 v[10:11], v[10:11], v[20:21] op_sel_hi:[1,0]
	v_pk_mul_f32 v[0:1], v[0:1], v[20:21] op_sel_hi:[1,0]
	v_pk_mul_f32 v[2:3], v[2:3], v[20:21] op_sel_hi:[1,0]
	v_pk_mul_f32 v[4:5], v[4:5], v[20:21] op_sel_hi:[1,0]
	s_waitcnt vmcnt(13)
	v_pk_mul_f32 v[12:13], v[168:169], v[12:13]
	v_pk_add_f32 v[16:17], v[136:137], 1.0 op_sel_hi:[1,0]
	v_pk_mul_f32 v[14:15], v[170:171], v[14:15]
	v_pk_fma_f32 v[12:13], v[16:17], v[12:13], v[152:153]
	v_pk_add_f32 v[16:17], v[138:139], 1.0 op_sel_hi:[1,0]
	v_cvt_pk_bf16_f32 v12, v12, v13
	v_pk_fma_f32 v[14:15], v[16:17], v[14:15], v[154:155]
	v_lshl_add_u64 v[16:17], v[44:45], 0, v[36:37]
	v_cvt_pk_bf16_f32 v13, v14, v15
	global_store_dwordx2 v[42:43], v[12:13], off
	s_nop 0
	v_lshl_add_u64 v[46:47], v[22:23], 0, v[36:37]
	s_nop 0
	s_waitcnt vmcnt(13)
	v_pk_mul_f32 v[8:9], v[172:173], v[8:9]
	s_nop 0
	s_waitcnt vmcnt(12)
	v_pk_add_f32 v[12:13], v[140:141], 1.0 op_sel_hi:[1,0]
	v_pk_mul_f32 v[10:11], v[174:175], v[10:11]
	v_lshl_add_u64 v[16:17], v[22:23], 0, v[38:39]
	s_waitcnt vmcnt(11)
	v_pk_fma_f32 v[8:9], v[12:13], v[8:9], v[156:157]
	v_pk_add_f32 v[12:13], v[142:143], 1.0 op_sel_hi:[1,0]
	v_cvt_pk_bf16_f32 v8, v8, v9
	v_pk_fma_f32 v[10:11], v[12:13], v[10:11], v[158:159]
	v_lshl_add_u64 v[12:13], v[44:45], 0, v[38:39]
	v_cvt_pk_bf16_f32 v9, v10, v11
	global_store_dwordx2 v[42:43], v[8:9], off offset:512
	s_nop 0
	s_waitcnt vmcnt(11)
	v_pk_mul_f32 v[0:1], v[176:177], v[0:1]
	s_nop 0
	v_pk_mul_f32 v[2:3], v[178:179], v[2:3]
	s_nop 0
	s_waitcnt vmcnt(10)
	v_pk_add_f32 v[8:9], v[144:145], 1.0 op_sel_hi:[1,0]
	v_lshl_add_u64 v[12:13], v[22:23], 0, v[40:41]
	s_waitcnt vmcnt(9)
	v_pk_fma_f32 v[0:1], v[8:9], v[0:1], v[160:161]
	v_pk_add_f32 v[8:9], v[146:147], 1.0 op_sel_hi:[1,0]
	v_cvt_pk_bf16_f32 v0, v0, v1
	v_pk_fma_f32 v[2:3], v[8:9], v[2:3], v[162:163]
	v_lshl_add_u64 v[8:9], v[44:45], 0, v[40:41]
	v_cvt_pk_bf16_f32 v1, v2, v3
	global_store_dwordx2 v[42:43], v[0:1], off offset:1024
	s_nop 0
	s_waitcnt vmcnt(9)
	v_pk_mul_f32 v[0:1], v[180:181], v[4:5]
	s_nop 0
	s_waitcnt vmcnt(8)
	v_pk_add_f32 v[4:5], v[148:149], 1.0 op_sel_hi:[1,0]
	s_nop 0
	s_waitcnt vmcnt(7)
	v_pk_fma_f32 v[0:1], v[4:5], v[0:1], v[164:165]
	v_pk_mul_f32 v[4:5], v[6:7], v[20:21] op_sel_hi:[1,0]
	v_cvt_pk_bf16_f32 v0, v0, v1
	v_pk_mul_f32 v[2:3], v[182:183], v[4:5]
	v_pk_add_f32 v[4:5], v[150:151], 1.0 op_sel_hi:[1,0]
	s_nop 0
	v_pk_fma_f32 v[2:3], v[4:5], v[2:3], v[166:167]
	s_nop 0
	v_cvt_pk_bf16_f32 v1, v2, v3
	global_store_dwordx2 v[42:43], v[0:1], off offset:1536
	s_andn2_b64 exec, exec, s[44:45]
	s_cbranch_execnz .LBB0_71

.LBB0_617:
	s_lshl_b32 s11, s1, 2
	s_lshl_b32 s12, s10, 2
	v_add_u32_e32 v22, s11, v6
	v_add_u32_e32 v20, s12, v5
	v_add_u32_e32 v24, s12, v9
	v_add_u32_e32 v26, s11, v10
	v_add_u32_e32 v28, s12, v13
	v_add_u32_e32 v30, s11, v14
	v_add_u32_e32 v32, s12, v17
	v_add_u32_e32 v34, s11, v18
	v_ashrrev_i32_e32 v23, 31, v22
	v_ashrrev_i32_e32 v21, 31, v20
	v_ashrrev_i32_e32 v27, 31, v26
	v_ashrrev_i32_e32 v25, 31, v24
	v_ashrrev_i32_e32 v31, 31, v30
	v_ashrrev_i32_e32 v29, 31, v28
	v_ashrrev_i32_e32 v35, 31, v34
	v_ashrrev_i32_e32 v33, 31, v32
	v_lshlrev_b64 v[22:23], 12, v[22:23]
	v_lshlrev_b64 v[20:21], 12, v[20:21]
	v_lshlrev_b64 v[24:25], 12, v[24:25]
	v_lshlrev_b64 v[26:27], 12, v[26:27]
	v_lshlrev_b64 v[28:29], 12, v[28:29]
	v_lshlrev_b64 v[30:31], 12, v[30:31]
	v_lshlrev_b64 v[32:33], 12, v[32:33]
	v_lshlrev_b64 v[34:35], 12, v[34:35]
	v_lshl_add_u64 v[22:23], v[2:3], 0, v[22:23]
	v_lshl_add_u64 v[20:21], v[2:3], 0, v[20:21]
	v_lshl_add_u64 v[26:27], v[2:3], 0, v[26:27]
	v_lshl_add_u64 v[24:25], v[2:3], 0, v[24:25]
	v_lshl_add_u64 v[30:31], v[2:3], 0, v[30:31]
	v_lshl_add_u64 v[28:29], v[2:3], 0, v[28:29]
	v_lshl_add_u64 v[34:35], v[2:3], 0, v[34:35]
	v_lshl_add_u64 v[32:33], v[2:3], 0, v[32:33]
	global_load_dword v37, v[22:23], off nt
	global_load_dword v40, v[20:21], off nt
	global_load_dword v41, v[26:27], off nt
	global_load_dword v42, v[24:25], off nt
	global_load_dword v43, v[30:31], off nt
	global_load_dword v44, v[28:29], off nt
	global_load_dword v45, v[34:35], off nt
	global_load_dword v46, v[32:33], off nt
	s_add_i32 s1, s1, 8
	s_add_i32 s10, s10, 8
	s_add_i32 s8, s8, -8
	v_add_u32_e32 v20, s11, v4
	v_add_u32_e32 v22, s12, v1
	v_add_u32_e32 v26, s12, v7
	v_add_u32_e32 v24, s11, v8
	v_add_u32_e32 v30, s12, v11
	v_add_u32_e32 v28, s11, v12
	v_add_u32_e32 v34, s12, v15
	v_add_u32_e32 v32, s11, v16
	s_cmp_lg_u32 s8, 0
	v_mad_u64_u32 v[20:21], s[12:13], v20, s66, v[0:1]
	v_mad_u64_u32 v[22:23], s[12:13], v22, s66, v[0:1]
	v_mad_u64_u32 v[24:25], s[12:13], v24, s66, v[0:1]
	v_mad_u64_u32 v[26:27], s[12:13], v26, s66, v[0:1]
	v_mad_u64_u32 v[28:29], s[12:13], v28, s66, v[0:1]
	v_mad_u64_u32 v[30:31], s[12:13], v30, s66, v[0:1]
	v_mad_u64_u32 v[32:33], s[12:13], v32, s66, v[0:1]
	v_mad_u64_u32 v[34:35], s[12:13], v34, s66, v[0:1]
	s_waitcnt vmcnt(7)
	ds_write_b32 v20, v37
	s_waitcnt vmcnt(6)
	ds_write_b32 v22, v40
	s_waitcnt vmcnt(5)
	ds_write_b32 v24, v41
	s_waitcnt vmcnt(4)
	ds_write_b32 v26, v42
	s_waitcnt vmcnt(3)
	ds_write_b32 v28, v43
	s_waitcnt vmcnt(2)
	ds_write_b32 v30, v44
	s_waitcnt vmcnt(1)
	ds_write_b32 v32, v45
	s_waitcnt vmcnt(0)
	ds_write_b32 v34, v46
	s_cbranch_scc1 .LBB0_617
	s_and_b64 s[10:11], s[28:29], exec
	s_cselect_b32 s1, 0x580000, 0
	v_readlane_b32 s8, v254, 9
	v_readlane_b32 s9, v254, 10
	s_add_u32 s1, s8, s1
	s_addc_u32 s8, s9, 0
	v_lshlrev_b32_e32 v0, 3, v19
	s_lshl_b32 s0, s0, 1
	v_and_b32_e32 v2, 56, v0
	s_add_u32 s0, s1, s0
	s_addc_u32 s1, s8, 0
	v_lshlrev_b32_e32 v192, 1, v2
	v_ashrrev_i32_e32 v4, 3, v19
	v_lshl_add_u64 v[0:1], s[0:1], 0, v[192:193]
	v_add_u32_e32 v3, s3, v4
	s_movk_i32 s0, 0x400
	v_cmp_gt_i32_e32 vcc, s0, v3
	v_mul_u32_u24_e32 v2, 0x104, v2
	v_readlane_b32 s10, v254, 11
	v_readlane_b32 s11, v254, 12
	v_readlane_b32 s12, v254, 13
	v_readlane_b32 s13, v254, 14
	v_readlane_b32 s14, v254, 15
	v_readlane_b32 s15, v254, 16
	v_readlane_b32 s16, v254, 17
	v_readlane_b32 s17, v254, 18
	v_readlane_b32 s18, v254, 19
	v_readlane_b32 s19, v254, 20
	v_readlane_b32 s20, v254, 21
	v_readlane_b32 s21, v254, 22
	v_readlane_b32 s22, v254, 23
	v_readlane_b32 s23, v254, 24
	s_waitcnt lgkmcnt(0)
	s_barrier
	s_and_saveexec_b64 s[0:1], vcc
	s_cbranch_execz .LBB0_620
	v_lshlrev_b32_e32 v4, 2, v4
	v_add3_u32 v8, 32, v4, v2
	v_add_u32_e32 v10, 0x400, v8
	ds_read2_b32 v[4:5], v8 offset1:65
	ds_read2_b32 v[6:7], v8 offset0:130 offset1:195
	ds_read2_b32 v[8:9], v10 offset0:4 offset1:69
	ds_read2_b32 v[10:11], v10 offset0:134 offset1:199
	s_movk_i32 s8, 0x1600
	s_waitcnt lgkmcnt(3)
	v_cvt_pk_bf16_f32 v4, v4, v5
	s_waitcnt lgkmcnt(2)
	v_cvt_pk_bf16_f32 v5, v6, v7
	s_waitcnt lgkmcnt(1)
	v_cvt_pk_bf16_f32 v6, v8, v9
	s_waitcnt lgkmcnt(0)
	v_cvt_pk_bf16_f32 v7, v10, v11
	v_mad_i64_i32 v[8:9], s[10:11], v3, s8, v[0:1]
	global_store_dwordx4 v[8:9], v[4:7], off

.LBB0_625:
	s_lshl_b32 s16, s0, 2
	s_lshl_b32 s17, s11, 2
	v_add_u32_e32 v20, s16, v6
	v_add_u32_e32 v22, s17, v5
	v_add_u32_e32 v26, s17, v9
	v_add_u32_e32 v24, s16, v10
	v_add_u32_e32 v30, s17, v13
	v_add_u32_e32 v28, s16, v14
	v_add_u32_e32 v34, s17, v17
	v_add_u32_e32 v32, s16, v18
	v_mad_i64_i32 v[20:21], s[12:13], v20, s26, v[2:3]
	v_mad_i64_i32 v[22:23], s[12:13], v22, s26, v[2:3]
	v_mad_i64_i32 v[24:25], s[12:13], v24, s26, v[2:3]
	v_mad_i64_i32 v[26:27], s[12:13], v26, s26, v[2:3]
	v_mad_i64_i32 v[28:29], s[12:13], v28, s26, v[2:3]
	v_mad_i64_i32 v[30:31], s[12:13], v30, s26, v[2:3]
	v_mad_i64_i32 v[32:33], s[12:13], v32, s26, v[2:3]
	v_mad_i64_i32 v[34:35], s[12:13], v34, s26, v[2:3]
	global_load_dword v37, v[20:21], off nt
	global_load_dword v40, v[22:23], off nt
	global_load_dword v41, v[24:25], off nt
	global_load_dword v42, v[26:27], off nt
	global_load_dword v43, v[28:29], off nt
	global_load_dword v44, v[30:31], off nt
	global_load_dword v45, v[32:33], off nt
	global_load_dword v46, v[34:35], off nt
	s_add_i32 s0, s0, 8
	s_add_i32 s11, s11, 8
	s_add_i32 s10, s10, -8
	v_add_u32_e32 v20, s16, v4
	v_add_u32_e32 v22, s17, v1
	v_add_u32_e32 v26, s17, v7
	v_add_u32_e32 v24, s16, v8
	v_add_u32_e32 v30, s17, v11
	v_add_u32_e32 v28, s16, v12
	v_add_u32_e32 v34, s17, v15
	v_add_u32_e32 v32, s16, v16
	s_cmp_lg_u32 s10, 0
	v_mad_u64_u32 v[20:21], s[12:13], v20, s66, v[0:1]
	v_mad_u64_u32 v[22:23], s[12:13], v22, s66, v[0:1]
	v_mad_u64_u32 v[24:25], s[12:13], v24, s66, v[0:1]
	v_mad_u64_u32 v[26:27], s[12:13], v26, s66, v[0:1]
	v_mad_u64_u32 v[28:29], s[12:13], v28, s66, v[0:1]
	v_mad_u64_u32 v[30:31], s[12:13], v30, s66, v[0:1]
	v_mad_u64_u32 v[32:33], s[12:13], v32, s66, v[0:1]
	v_mad_u64_u32 v[34:35], s[12:13], v34, s66, v[0:1]
	s_waitcnt vmcnt(7)
	ds_write_b32 v20, v37
	s_waitcnt vmcnt(6)
	ds_write_b32 v22, v40
	s_waitcnt vmcnt(5)
	ds_write_b32 v24, v41
	s_waitcnt vmcnt(4)
	ds_write_b32 v26, v42
	s_waitcnt vmcnt(3)
	ds_write_b32 v28, v43
	s_waitcnt vmcnt(2)
	ds_write_b32 v30, v44
	s_waitcnt vmcnt(1)
	ds_write_b32 v32, v45
	s_waitcnt vmcnt(0)
	ds_write_b32 v34, v46
	s_cbranch_scc1 .LBB0_625
	v_readlane_b32 s40, v254, 38
	v_readlane_b32 s54, v254, 52
	v_readlane_b32 s55, v254, 53
	s_add_u32 s0, s54, s1
	s_addc_u32 s1, s55, 0
	s_and_b32 s8, 0xffff, s8
	v_lshlrev_b32_e32 v0, 3, v19
	s_lshl_b32 s3, s3, 1
	v_and_b32_e32 v2, 56, v0
	s_add_u32 s0, s0, s3
	s_addc_u32 s1, s1, 0
	v_lshlrev_b32_e32 v192, 1, v2
	v_ashrrev_i32_e32 v3, 3, v19
	v_lshl_add_u64 v[0:1], s[0:1], 0, v[192:193]
	v_add_u32_e32 v4, s8, v3
	s_movk_i32 s0, 0xb00
	v_cmp_gt_i32_e32 vcc, s0, v4
	v_mul_u32_u24_e32 v2, 0x104, v2
	v_readlane_b32 s41, v254, 39
	v_readlane_b32 s42, v254, 40
	v_readlane_b32 s43, v254, 41
	v_readlane_b32 s44, v254, 42
	v_readlane_b32 s45, v254, 43
	v_readlane_b32 s46, v254, 44
	v_readlane_b32 s47, v254, 45
	v_readlane_b32 s48, v254, 46
	v_readlane_b32 s49, v254, 47
	v_readlane_b32 s50, v254, 48
	v_readlane_b32 s51, v254, 49
	v_readlane_b32 s52, v254, 50
	v_readlane_b32 s53, v254, 51
	s_waitcnt lgkmcnt(0)
	s_barrier
	s_and_saveexec_b64 s[0:1], vcc
	s_cbranch_execz .LBB0_628
	v_lshlrev_b32_e32 v3, 2, v3
	v_lshlrev_b32_e32 v4, 1, v4
	v_add3_u32 v3, 32, v3, v2
	v_and_b32_e32 v12, 0xffffffe0, v4
	ds_read2_b32 v[4:5], v3 offset1:65
	ds_read2_b32 v[6:7], v3 offset0:130 offset1:195
	v_add_u32_e32 v3, 0x400, v3
	ds_read2_b32 v[8:9], v3 offset0:4 offset1:69
	ds_read2_b32 v[10:11], v3 offset0:134 offset1:199
	v_bfe_u32 v13, v19, 3, 4
	v_or3_b32 v12, v13, v12, 16
	v_ashrrev_i32_e32 v13, 31, v12
	s_waitcnt lgkmcnt(3)
	v_cvt_pk_bf16_f32 v4, v4, v5
	s_waitcnt lgkmcnt(2)
	v_cvt_pk_bf16_f32 v5, v6, v7
	s_waitcnt lgkmcnt(1)
	v_cvt_pk_bf16_f32 v6, v8, v9
	v_lshlrev_b64 v[8:9], 11, v[12:13]
	s_waitcnt lgkmcnt(0)
	v_cvt_pk_bf16_f32 v7, v10, v11
	v_lshl_add_u64 v[8:9], v[0:1], 0, v[8:9]
	global_store_dwordx4 v[8:9], v[4:7], off

.LBB0_634:
	s_lshl_b32 s16, s0, 2
	s_lshl_b32 s17, s11, 2
	v_add_u32_e32 v20, s16, v6
	v_add_u32_e32 v22, s17, v5
	v_add_u32_e32 v26, s17, v9
	v_add_u32_e32 v24, s16, v10
	v_add_u32_e32 v30, s17, v13
	v_add_u32_e32 v28, s16, v14
	v_add_u32_e32 v34, s17, v17
	v_add_u32_e32 v32, s16, v18
	v_mad_i64_i32 v[20:21], s[12:13], v20, s26, v[2:3]
	v_mad_i64_i32 v[22:23], s[12:13], v22, s26, v[2:3]
	v_mad_i64_i32 v[24:25], s[12:13], v24, s26, v[2:3]
	v_mad_i64_i32 v[26:27], s[12:13], v26, s26, v[2:3]
	v_mad_i64_i32 v[28:29], s[12:13], v28, s26, v[2:3]
	v_mad_i64_i32 v[30:31], s[12:13], v30, s26, v[2:3]
	v_mad_i64_i32 v[32:33], s[12:13], v32, s26, v[2:3]
	v_mad_i64_i32 v[34:35], s[12:13], v34, s26, v[2:3]
	global_load_dword v37, v[20:21], off nt
	global_load_dword v40, v[22:23], off nt
	global_load_dword v41, v[24:25], off nt
	global_load_dword v42, v[26:27], off nt
	global_load_dword v43, v[28:29], off nt
	global_load_dword v44, v[30:31], off nt
	global_load_dword v45, v[32:33], off nt
	global_load_dword v46, v[34:35], off nt
	s_add_i32 s0, s0, 8
	s_add_i32 s11, s11, 8
	s_add_i32 s10, s10, -8
	v_add_u32_e32 v20, s16, v4
	v_add_u32_e32 v22, s17, v1
	v_add_u32_e32 v26, s17, v7
	v_add_u32_e32 v24, s16, v8
	v_add_u32_e32 v30, s17, v11
	v_add_u32_e32 v28, s16, v12
	v_add_u32_e32 v34, s17, v15
	v_add_u32_e32 v32, s16, v16
	s_cmp_lg_u32 s10, 0
	v_mad_u64_u32 v[20:21], s[12:13], v20, s66, v[0:1]
	v_mad_u64_u32 v[22:23], s[12:13], v22, s66, v[0:1]
	v_mad_u64_u32 v[24:25], s[12:13], v24, s66, v[0:1]
	v_mad_u64_u32 v[26:27], s[12:13], v26, s66, v[0:1]
	v_mad_u64_u32 v[28:29], s[12:13], v28, s66, v[0:1]
	v_mad_u64_u32 v[30:31], s[12:13], v30, s66, v[0:1]
	v_mad_u64_u32 v[32:33], s[12:13], v32, s66, v[0:1]
	v_mad_u64_u32 v[34:35], s[12:13], v34, s66, v[0:1]
	s_waitcnt vmcnt(7)
	ds_write_b32 v20, v37
	s_waitcnt vmcnt(6)
	ds_write_b32 v22, v40
	s_waitcnt vmcnt(5)
	ds_write_b32 v24, v41
	s_waitcnt vmcnt(4)
	ds_write_b32 v26, v42
	s_waitcnt vmcnt(3)
	ds_write_b32 v28, v43
	s_waitcnt vmcnt(2)
	ds_write_b32 v30, v44
	s_waitcnt vmcnt(1)
	ds_write_b32 v32, v45
	s_waitcnt vmcnt(0)
	ds_write_b32 v34, v46
	s_cbranch_scc1 .LBB0_634
	v_readlane_b32 s40, v254, 38
	v_readlane_b32 s54, v254, 52
	v_readlane_b32 s55, v254, 53
	s_add_u32 s0, s54, s1
	s_addc_u32 s1, s55, 0
	s_and_b32 s8, 0xffff, s8
	v_lshlrev_b32_e32 v0, 3, v19
	s_lshl_b32 s3, s3, 1
	v_and_b32_e32 v2, 56, v0
	s_add_u32 s0, s0, s3
	s_addc_u32 s1, s1, 0
	v_lshlrev_b32_e32 v192, 1, v2
	v_ashrrev_i32_e32 v3, 3, v19
	v_lshl_add_u64 v[0:1], s[0:1], 0, v[192:193]
	v_add_u32_e32 v4, s8, v3
	s_movk_i32 s0, 0xb00
	v_cmp_gt_i32_e32 vcc, s0, v4
	v_mul_u32_u24_e32 v2, 0x104, v2
	v_readlane_b32 s41, v254, 39
	v_readlane_b32 s42, v254, 40
	v_readlane_b32 s43, v254, 41
	v_readlane_b32 s44, v254, 42
	v_readlane_b32 s45, v254, 43
	v_readlane_b32 s46, v254, 44
	v_readlane_b32 s47, v254, 45
	v_readlane_b32 s48, v254, 46
	v_readlane_b32 s49, v254, 47
	v_readlane_b32 s50, v254, 48
	v_readlane_b32 s51, v254, 49
	v_readlane_b32 s52, v254, 50
	v_readlane_b32 s53, v254, 51
	s_waitcnt lgkmcnt(0)
	s_barrier
	s_and_saveexec_b64 s[0:1], vcc
	s_cbranch_execz .LBB0_637
	v_lshlrev_b32_e32 v3, 2, v3
	v_add3_u32 v3, 32, v3, v2
	v_lshlrev_b32_e32 v12, 1, v4
	ds_read2_b32 v[4:5], v3 offset1:65
	ds_read2_b32 v[6:7], v3 offset0:130 offset1:195
	v_add_u32_e32 v3, 0x400, v3
	ds_read2_b32 v[8:9], v3 offset0:4 offset1:69
	ds_read2_b32 v[10:11], v3 offset0:134 offset1:199
	v_bfe_u32 v13, v19, 3, 4
	s_movk_i32 s3, 0xffe0
	v_and_or_b32 v12, v12, s3, v13
	v_ashrrev_i32_e32 v13, 31, v12
	s_waitcnt lgkmcnt(3)
	v_cvt_pk_bf16_f32 v4, v4, v5
	s_waitcnt lgkmcnt(2)
	v_cvt_pk_bf16_f32 v5, v6, v7
	s_waitcnt lgkmcnt(1)
	v_cvt_pk_bf16_f32 v6, v8, v9
	v_lshlrev_b64 v[8:9], 11, v[12:13]
	s_waitcnt lgkmcnt(0)
	v_cvt_pk_bf16_f32 v7, v10, v11
	v_lshl_add_u64 v[8:9], v[0:1], 0, v[8:9]
	global_store_dwordx4 v[8:9], v[4:7], off

.LBB0_643:
	s_lshl_b32 s12, s0, 2
	s_lshl_b32 s13, s11, 2
	v_add_u32_e32 v22, s12, v6
	v_add_u32_e32 v20, s13, v5
	v_add_u32_e32 v24, s13, v9
	v_add_u32_e32 v26, s12, v10
	v_add_u32_e32 v28, s13, v13
	v_add_u32_e32 v30, s12, v14
	v_add_u32_e32 v32, s13, v17
	v_add_u32_e32 v34, s12, v18
	v_ashrrev_i32_e32 v23, 31, v22
	v_ashrrev_i32_e32 v21, 31, v20
	v_ashrrev_i32_e32 v27, 31, v26
	v_ashrrev_i32_e32 v25, 31, v24
	v_ashrrev_i32_e32 v31, 31, v30
	v_ashrrev_i32_e32 v29, 31, v28
	v_ashrrev_i32_e32 v35, 31, v34
	v_ashrrev_i32_e32 v33, 31, v32
	v_lshlrev_b64 v[22:23], 12, v[22:23]
	v_lshlrev_b64 v[20:21], 12, v[20:21]
	v_lshlrev_b64 v[24:25], 12, v[24:25]
	v_lshlrev_b64 v[26:27], 12, v[26:27]
	v_lshlrev_b64 v[28:29], 12, v[28:29]
	v_lshlrev_b64 v[30:31], 12, v[30:31]
	v_lshlrev_b64 v[32:33], 12, v[32:33]
	v_lshlrev_b64 v[34:35], 12, v[34:35]
	v_lshl_add_u64 v[22:23], v[2:3], 0, v[22:23]
	v_lshl_add_u64 v[20:21], v[2:3], 0, v[20:21]
	v_lshl_add_u64 v[26:27], v[2:3], 0, v[26:27]
	v_lshl_add_u64 v[24:25], v[2:3], 0, v[24:25]
	v_lshl_add_u64 v[30:31], v[2:3], 0, v[30:31]
	v_lshl_add_u64 v[28:29], v[2:3], 0, v[28:29]
	v_lshl_add_u64 v[34:35], v[2:3], 0, v[34:35]
	v_lshl_add_u64 v[32:33], v[2:3], 0, v[32:33]
	global_load_dword v37, v[22:23], off nt
	global_load_dword v40, v[20:21], off nt
	global_load_dword v41, v[26:27], off nt
	global_load_dword v42, v[24:25], off nt
	global_load_dword v43, v[30:31], off nt
	global_load_dword v44, v[28:29], off nt
	global_load_dword v45, v[34:35], off nt
	global_load_dword v46, v[32:33], off nt
	s_add_i32 s0, s0, 8
	s_add_i32 s11, s11, 8
	s_add_i32 s10, s10, -8
	v_add_u32_e32 v20, s12, v4
	v_add_u32_e32 v22, s13, v1
	v_add_u32_e32 v26, s13, v7
	v_add_u32_e32 v24, s12, v8
	v_add_u32_e32 v30, s13, v11
	v_add_u32_e32 v28, s12, v12
	v_add_u32_e32 v34, s13, v15
	v_add_u32_e32 v32, s12, v16
	s_cmp_lg_u32 s10, 0
	v_mad_u64_u32 v[20:21], s[12:13], v20, s66, v[0:1]
	v_mad_u64_u32 v[22:23], s[12:13], v22, s66, v[0:1]
	v_mad_u64_u32 v[24:25], s[12:13], v24, s66, v[0:1]
	v_mad_u64_u32 v[26:27], s[12:13], v26, s66, v[0:1]
	v_mad_u64_u32 v[28:29], s[12:13], v28, s66, v[0:1]
	v_mad_u64_u32 v[30:31], s[12:13], v30, s66, v[0:1]
	v_mad_u64_u32 v[32:33], s[12:13], v32, s66, v[0:1]
	v_mad_u64_u32 v[34:35], s[12:13], v34, s66, v[0:1]
	s_waitcnt vmcnt(7)
	ds_write_b32 v20, v37
	s_waitcnt vmcnt(6)
	ds_write_b32 v22, v40
	s_waitcnt vmcnt(5)
	ds_write_b32 v24, v41
	s_waitcnt vmcnt(4)
	ds_write_b32 v26, v42
	s_waitcnt vmcnt(3)
	ds_write_b32 v28, v43
	s_waitcnt vmcnt(2)
	ds_write_b32 v30, v44
	s_waitcnt vmcnt(1)
	ds_write_b32 v32, v45
	s_waitcnt vmcnt(0)
	ds_write_b32 v34, v46
	s_cbranch_scc1 .LBB0_643
	v_readlane_b32 s40, v254, 38
	s_lshl_b32 s0, s1, 1
	v_readlane_b32 s52, v254, 50
	v_readlane_b32 s53, v254, 51
	s_add_u32 s0, s52, s0
	s_addc_u32 s1, s53, 0
	v_lshlrev_b32_e32 v0, 3, v19
	s_lshl_b32 s8, s8, 1
	v_and_b32_e32 v4, 56, v0
	s_add_u32 s0, s0, s8
	s_addc_u32 s1, s1, 0
	v_lshlrev_b32_e32 v192, 1, v4
	v_ashrrev_i32_e32 v3, 3, v19
	v_lshl_add_u64 v[0:1], s[0:1], 0, v[192:193]
	v_add_u32_e32 v2, s3, v3
	s_movk_i32 s0, 0x400
	v_cmp_gt_i32_e32 vcc, s0, v2
	v_mul_u32_u24_e32 v4, 0x104, v4
	v_readlane_b32 s41, v254, 39
	v_readlane_b32 s42, v254, 40
	v_readlane_b32 s43, v254, 41
	v_readlane_b32 s44, v254, 42
	v_readlane_b32 s45, v254, 43
	v_readlane_b32 s46, v254, 44
	v_readlane_b32 s47, v254, 45
	v_readlane_b32 s48, v254, 46
	v_readlane_b32 s49, v254, 47
	v_readlane_b32 s50, v254, 48
	v_readlane_b32 s51, v254, 49
	v_readlane_b32 s54, v254, 52
	v_readlane_b32 s55, v254, 53
	s_waitcnt lgkmcnt(0)
	s_barrier
	s_and_saveexec_b64 s[0:1], vcc
	s_cbranch_execz .LBB0_646
	v_lshlrev_b32_e32 v3, 2, v3
	v_add3_u32 v3, 32, v3, v4
	ds_read2_b32 v[6:7], v3 offset1:65
	ds_read2_b32 v[8:9], v3 offset0:130 offset1:195
	v_add_u32_e32 v3, 0x400, v3
	ds_read2_b32 v[10:11], v3 offset0:4 offset1:69
	ds_read2_b32 v[12:13], v3 offset0:134 offset1:199
	v_ashrrev_i32_e32 v3, 31, v2
	v_lshlrev_b64 v[2:3], 11, v[2:3]
	s_waitcnt lgkmcnt(3)
	v_cvt_pk_bf16_f32 v6, v6, v7
	s_waitcnt lgkmcnt(2)
	v_cvt_pk_bf16_f32 v7, v8, v9
	s_waitcnt lgkmcnt(1)
	v_cvt_pk_bf16_f32 v8, v10, v11
	s_waitcnt lgkmcnt(0)
	v_cvt_pk_bf16_f32 v9, v12, v13
	v_lshl_add_u64 v[2:3], v[0:1], 0, v[2:3]
	global_store_dwordx4 v[2:3], v[6:9], off

.LBB0_653:
	v_lshl_add_u64 v[14:15], v[4:5], 0, s[40:41]
	global_load_dword v14, v[14:15], off nt
	v_cndmask_b32_e64 v15, 0, 1, s[10:11]
	v_cmp_ne_u32_e64 s[0:1], 1, v15
	s_andn2_b64 vcc, exec, s[10:11]
	s_cbranch_vccnz .LBB0_655
	global_load_dword v15, v[10:11], off nt
	s_waitcnt vmcnt(0)
	v_mul_f32_e32 v14, v14, v15
.LBB0_655:
	v_lshl_add_u64 v[16:17], v[6:7], 0, s[40:41]
	global_load_dword v15, v[16:17], off nt
	s_and_b64 vcc, exec, s[0:1]
	s_waitcnt vmcnt(1)
	ds_write_b32 v13, v14
	s_cbranch_vccnz .LBB0_657
	global_load_dword v14, v[8:9], off nt
	s_waitcnt vmcnt(0)
	v_mul_f32_e32 v15, v15, v14
.LBB0_657:
	v_lshl_add_u64 v[16:17], v[2:3], 0, s[40:41]
	global_load_dword v14, v[16:17], off nt
	s_and_b64 vcc, exec, s[0:1]
	s_waitcnt vmcnt(1)
	ds_write_b32 v13, v15 offset:1040
	s_cbranch_vccnz .LBB0_659
	global_load_dword v15, v[8:9], off offset:16 nt
	s_waitcnt vmcnt(0)
	v_mul_f32_e32 v14, v14, v15
.LBB0_659:
	v_lshl_add_u64 v[16:17], v[0:1], 0, s[40:41]
	global_load_dword v15, v[16:17], off nt
	s_and_b64 vcc, exec, s[0:1]
	s_waitcnt vmcnt(1)
	ds_write_b32 v13, v14 offset:2080
	s_cbranch_vccnz .LBB0_652
	global_load_dword v14, v[8:9], off offset:32 nt
	s_waitcnt vmcnt(0)
	v_mul_f32_e32 v15, v15, v14
	s_branch .LBB0_652

.LBB0_670:
	v_lshl_add_u64 v[12:13], v[4:5], 0, s[40:41]
	global_load_dword v12, v[12:13], off nt
	v_cndmask_b32_e64 v13, 0, 1, s[62:63]
	v_cmp_ne_u32_e64 s[0:1], 1, v13
	s_andn2_b64 vcc, exec, s[62:63]
	s_cbranch_vccnz .LBB0_672
	global_load_dword v13, v[8:9], off offset:-32
	s_waitcnt vmcnt(0)
	v_mul_f32_e32 v12, v12, v13
.LBB0_672:
	v_lshl_add_u64 v[14:15], v[6:7], 0, s[40:41]
	global_load_dword v13, v[14:15], off nt
	s_and_b64 vcc, exec, s[0:1]
	s_waitcnt vmcnt(1)
	ds_write_b32 v11, v12
	s_cbranch_vccnz .LBB0_674
	global_load_dword v12, v[8:9], off offset:-16
	s_waitcnt vmcnt(0)
	v_mul_f32_e32 v13, v13, v12
.LBB0_674:
	v_lshl_add_u64 v[14:15], v[2:3], 0, s[40:41]
	global_load_dword v12, v[14:15], off nt
	s_and_b64 vcc, exec, s[0:1]
	s_waitcnt vmcnt(1)
	ds_write_b32 v11, v13 offset:1040
	s_cbranch_vccnz .LBB0_676
	global_load_dword v13, v[8:9], off nt
	s_waitcnt vmcnt(0)
	v_mul_f32_e32 v12, v12, v13
.LBB0_676:
	v_lshl_add_u64 v[14:15], v[0:1], 0, s[40:41]
	global_load_dword v13, v[14:15], off nt
	s_and_b64 vcc, exec, s[0:1]
	s_waitcnt vmcnt(1)
	ds_write_b32 v11, v12 offset:2080
	s_cbranch_vccnz .LBB0_669
	global_load_dword v12, v[8:9], off offset:16 nt
	s_waitcnt vmcnt(0)
	v_mul_f32_e32 v13, v13, v12
	s_branch .LBB0_669

.LBB0_687:
	v_mov_b32_e32 v10, 0
	v_mov_b32_e32 v11, 0
	s_and_saveexec_b64 s[2:3], vcc
	s_cbranch_execz .LBB0_689
	v_lshl_add_u64 v[12:13], v[6:7], 0, s[42:43]
	global_load_dword v11, v[12:13], off nt
.LBB0_689:
	s_or_b64 exec, exec, s[2:3]
	s_waitcnt vmcnt(0)
	ds_write_b32 v9, v11
	s_and_saveexec_b64 s[2:3], vcc
	s_cbranch_execz .LBB0_691
	v_lshl_add_u64 v[10:11], v[4:5], 0, s[42:43]
	global_load_dword v10, v[10:11], off nt
.LBB0_691:
	s_or_b64 exec, exec, s[2:3]
	s_waitcnt vmcnt(0)
	ds_write_b32 v9, v10 offset:1040
	v_mov_b32_e32 v10, 0
	v_mov_b32_e32 v11, 0
	s_and_saveexec_b64 s[2:3], vcc
	s_cbranch_execz .LBB0_693
	v_lshl_add_u64 v[12:13], v[2:3], 0, s[42:43]
	global_load_dword v11, v[12:13], off nt
.LBB0_693:
	s_or_b64 exec, exec, s[2:3]
	s_waitcnt vmcnt(0)
	ds_write_b32 v9, v11 offset:2080
	s_and_saveexec_b64 s[2:3], vcc
	s_cbranch_execz .LBB0_686
	v_lshl_add_u64 v[10:11], v[0:1], 0, s[42:43]
	global_load_dword v10, v[10:11], off nt
	s_branch .LBB0_686
